# v56 + one static s_setprio 1 for waves 4-7 (heavier causal row blocks) during the SSD phase
# baseline (speedup 1.0000x reference)
; #define LAS __attribute__((address_space(3)))
; __device__ __forceinline__ void ssd_phase(const bf16_t* XBC, const float* DT  , const ss_t* SSq, const float* dtb, const bf16_t* Z, const float* a_log, const float* d_skip, bf16_t* YS, LAS unsigned char* lds, int tid, int wid, int lane, int bid, int G) {
;     const int fr = lane & 15, fq = lane >> 4;
;     LAS bf16_t* Ct = (LAS bf16_t*)(lds + SS_CT); LAS bf16_t* Bt = (LAS bf16_t*)(lds + SS_BT); LAS bf16_t* XT = (LAS bf16_t*)(lds + SS_XT); LAS bf16_t* XW = (LAS bf16_t*)(lds + SS_XW);
;     LAS bf16_t* Sin = (LAS bf16_t*)(lds + SS_SIN); LAS float* csbuf = (LAS float*)(lds + SS_CS);
;     for (int w = bid; w < 256; w += G) {
;         const int b = w >> 6, h = w & 63, g = h >> 3;
;         const float A = -expf(a_log[h]), Dh = d_skip[h], dtbh = dtb[h];
;         f32x4 Sacc[4];
; #pragma unroll
;         for (int pt = 0; pt < 4; ++pt) Sacc[pt] = (f32x4){0.f, 0.f, 0.f, 0.f};
;         u32x4 cr[4], br[4], xr2[2]; float d0 = 0.f, d1 = 0.f;
;         const unsigned voffC = (unsigned)(((tid >> 4) * SSD_CONV + 5120 + g * 128 + (tid & 15) * 8) * 2), voffX = (unsigned)(((tid & 127) * SSD_CONV + h * 64 + (tid >> 7) * 8) * 2);
;     ...
;             const int lrow = 16 * wid + fr; const float csl = csv[lrow];
;             bf16x8 Cfr[4];
; #pragma unroll
;             for (int ks = 0; ks < 4; ++ks) Cfr[ks] = *(const LAS bf16x8*)(Ct + lrow * SS_RS + 32 * ks + 8 * fq);
;             unsigned gp[8][2];
; #pragma unroll
;             for (int t = 0; t < 8; ++t) {
;                 if (t <= wid) {
;                     f32x4 acc = (f32x4){0.f, 0.f, 0.f, 0.f};
; #pragma unroll
;                     for (int ks = 0; ks < 4; ++ks) { const bf16x8 bfr = *(const LAS bf16x8*)(Bt + (16 * t + fr) * SS_RS + 32 * ks + 8 * fq); acc = __builtin_amdgcn_mfma_f32_16x16x32_bf16(bfr, Cfr[ks], acc, 0, 0, 0); }
;                     const f32x4 cs4 = *(const LAS f32x4*)(csv + 16 * t + 4 * fq); float v[4];
; #pragma unroll
;                     for (int r = 0; r < 4; ++r) { const int sx = 16 * t + 4 * fq + r; v[r] = (sx <= lrow) ? acc[r] * __expf(csl - cs4[r]) : 0.f; }
;                     gp[t][0] = cvt_pk_bf16(v[0], v[1]); gp[t][1] = cvt_pk_bf16(v[2], v[3]);
;                 } else { gp[t][0] = 0u; gp[t][1] = 0u; }
;                 __builtin_amdgcn_sched_barrier(0);
.Lsge_done:
	s_sub_i32 s30, 11, s95
	s_cmp_gt_i32 s95, 3
	s_cselect_b32 s95, s30, s95
	s_cbranch_scc0 .Lssd_np
	s_setprio 1
.Lssd_np:
	s_load_dwordx2 s[6:7], s[92:93], 0xe8
	v_writelane_b32 v255, s76, 6
	v_writelane_b32 v255, s72, 7
	v_ashrrev_i32_e32 v5, 4, v212
	s_waitcnt lgkmcnt(0)
	v_lshlrev_b32_e32 v3, 3, v212
	v_writelane_b32 v255, s73, 8
	v_writelane_b32 v255, s74, 9
	v_mul_lo_u32 v2, v5, s83
	v_and_b32_e32 v6, 0x78, v3
	v_writelane_b32 v255, s75, 10
	s_add_u32 s2, s6, 0x1ac00000
	v_or_b32_e32 v7, v2, v6
	v_lshlrev_b32_e32 v2, 4, v211
	v_mov_b32_e32 v3, v0
	v_writelane_b32 v255, s2, 11
	s_addc_u32 s2, s7, 0
	v_lshrrev_b32_e32 v4, 4, v211
	v_lshl_add_u64 v[2:3], s[6:7], 0, v[2:3]
	s_mov_b64 s[6:7], 0x20e30000
	v_add_u32_e32 v15, 0x400, v212
	v_lshl_add_u64 v[108:109], v[2:3], 0, s[6:7]
	v_lshlrev_b32_e32 v3, 3, v4
	v_lshl_add_u32 v2, v6, 1, 0
	s_movk_i32 s28, 0x110
	v_lshrrev_b32_e32 v15, 4, v15
	v_and_b32_e32 v8, -8, v5
	v_mad_u64_u32 v[112:113], s[18:19], v5, s28, v[2:3]
	v_add_u32_e32 v5, 0x200, v212
	v_mad_u64_u32 v[116:117], s[18:19], v15, s28, v[2:3]
	v_add_u32_e32 v15, 0x600, v212
	v_ashrrev_i32_e32 v5, 4, v5
	v_lshrrev_b32_e32 v15, 4, v15
	v_mad_u64_u32 v[114:115], s[18:19], v5, s28, v[2:3]
	v_mad_u64_u32 v[118:119], s[18:19], v15, s28, v[2:3]
	s_movk_i32 s18, 0x88
	v_and_b32_e32 v107, 0x7f, v212
	v_mul_lo_u32 v2, v8, s18
	v_mad_u32_u24 v121, v107, s83, v8
	v_add_u32_e32 v6, 0x88, v107
	v_readlane_b32 s20, v254, 4
	v_add_lshl_u32 v8, v2, v107, 1
	v_readlane_b32 s29, v254, 5
	v_add_lshl_u32 v15, v2, v6, 1
	v_add_u32_e32 v117, s20, v8
	v_add_u32_e32 v113, s29, v8
	v_add_u32_e32 v8, 0x110, v2
	v_add_u32_e32 v115, s29, v15
	v_add_u32_e32 v119, s20, v15
	v_add_lshl_u32 v15, v8, v107, 1
	v_add_lshl_u32 v8, v8, v6, 1
	v_add_u32_e32 v171, s29, v8
	v_add_u32_e32 v173, s20, v8
	v_add_u32_e32 v8, 0x220, v2
	v_add_u32_e32 v170, s29, v15
	v_add_u32_e32 v172, s20, v15
	v_add_lshl_u32 v15, v8, v107, 1
	v_add_lshl_u32 v8, v8, v6, 1
	v_add_u32_e32 v2, 0x330, v2
	v_add_u32_e32 v175, s29, v8
	v_add_u32_e32 v177, s20, v8
	v_add_lshl_u32 v8, v2, v107, 1
	v_add_lshl_u32 v2, v2, v6, 1
	v_add_u32_e32 v179, s29, v2
	v_add_u32_e32 v181, s20, v2
	v_and_b32_e32 v2, 0x1ffffff8, v5
	s_cmp_gt_u32 s38, 63
	v_mul_lo_u32 v2, v2, s18
	v_writelane_b32 v255, s2, 12
	s_cselect_b64 s[2:3], -1, 0
	s_cmp_lt_u32 s38, 64
	v_add_lshl_u32 v5, v2, v107, 1
	v_and_b32_e32 v1, 15, v212
	s_cselect_b64 s[8:9], -1, 0
	v_add_u32_e32 v178, s29, v8
	v_add_u32_e32 v180, s20, v8
	v_add_u32_e32 v182, s29, v5
	v_add_lshl_u32 v8, v2, v6, 1
	v_add_u32_e32 v184, s20, v5
	v_add_u32_e32 v5, 0x110, v2
	v_writelane_b32 v255, s8, 13
	v_lshl_or_b32 v110, s95, 4, v1
	v_lshlrev_b32_e32 v165, 2, v4
	v_add_u32_e32 v183, s29, v8
	v_add_u32_e32 v185, s20, v8
	v_add_lshl_u32 v8, v5, v107, 1
	v_add_lshl_u32 v5, v5, v6, 1
	v_writelane_b32 v255, s9, 14
	v_add_u32_e32 v187, s29, v5
	v_add_u32_e32 v189, s20, v5
	v_add_u32_e32 v5, 0x220, v2
	v_cmp_gt_i32_e64 s[18:19], v165, v110
	v_add_u32_e32 v186, s29, v8
	v_add_u32_e32 v188, s20, v8
	v_add_lshl_u32 v8, v5, v107, 1
	v_add_lshl_u32 v5, v5, v6, 1
	v_add_u32_e32 v2, 0x330, v2
	v_writelane_b32 v255, s18, 15
	v_add_u32_e32 v191, s29, v5
	v_add_u32_e32 v193, s20, v5
	v_add_lshl_u32 v5, v2, v107, 1
	v_add_lshl_u32 v2, v2, v6, 1
	v_writelane_b32 v255, s19, 16
	v_cmp_lt_i32_e64 s[18:19], v165, v110
	v_add_u32_e32 v195, s29, v2
	v_add_u32_e32 v214, s20, v2
	v_writelane_b32 v255, s18, 17
	v_or_b32_e32 v2, 2, v165
	v_and_b32_e32 v10, 48, v212
	v_writelane_b32 v255, s19, 18
	v_cmp_gt_i32_e64 s[18:19], v2, v110
	v_or_b32_e32 v2, 3, v165
	v_add_u32_e32 v167, s20, v10
	v_writelane_b32 v255, s18, 19
	v_add_u32_e32 v176, s20, v15
	v_add_u32_e32 v192, s20, v8
	v_writelane_b32 v255, s19, 20
	v_cmp_gt_i32_e64 s[18:19], v2, v110
	v_or_b32_e32 v2, 16, v165
	v_add_u32_e32 v213, s20, v5
	v_writelane_b32 v255, s18, 21
	s_mov_b32 s36, s95
	v_readlane_b32 s6, v254, 2
	v_writelane_b32 v255, s19, 22
	v_cmp_gt_i32_e64 s[18:19], v2, v110
	v_or_b32_e32 v2, 17, v165
	s_mov_b32 s31, s94
	v_writelane_b32 v255, s18, 23
	v_lshl_add_u32 v153, v211, 3, s6
	s_lshl_b32 s6, s95, 5
	v_writelane_b32 v255, s19, 24
	v_cmp_gt_i32_e64 s[18:19], v2, v110
	v_or_b32_e32 v2, 18, v165
	v_readlane_b32 s8, v254, 3
	v_writelane_b32 v255, s18, 25
	s_add_i32 s7, s8, s6
	s_add_i32 s6, s6, 0
	v_writelane_b32 v255, s19, 26
	v_cmp_gt_i32_e64 s[18:19], v2, v110
	v_or_b32_e32 v2, 19, v165
	s_mov_b64 s[34:35], s[92:93]
	v_writelane_b32 v255, s18, 27
	s_cmp_gt_i32 s95, -1
	v_mov_b32_e32 v12, 0x1100
	v_writelane_b32 v255, s19, 28
	v_cmp_gt_i32_e64 s[18:19], v2, v110
	v_or_b32_e32 v2, 32, v165
	v_cmp_gt_i32_e64 s[20:21], v2, v110
	v_writelane_b32 v255, s18, 29
	v_or_b32_e32 v2, 33, v165
	v_mov_b32_e32 v13, 0x2200
	v_writelane_b32 v255, s19, 30
	v_writelane_b32 v255, s20, 31
	s_cselect_b64 s[94:95], -1, 0
	s_cmp_gt_i32 s36, 0
	v_writelane_b32 v255, s21, 32
	v_cmp_gt_i32_e64 s[20:21], v2, v110
	v_or_b32_e32 v2, 34, v165
	v_cmp_gt_i32_e64 s[40:41], v2, v110
	v_or_b32_e32 v2, 35, v165
	v_cmp_gt_i32_e64 s[42:43], v2, v110
	v_or_b32_e32 v2, 48, v165
	v_cmp_gt_i32_e64 s[44:45], v2, v110
	v_or_b32_e32 v2, 49, v165
	v_cmp_gt_i32_e64 s[46:47], v2, v110
	v_or_b32_e32 v2, 50, v165
	v_writelane_b32 v255, s20, 33
	v_cmp_gt_i32_e64 s[48:49], v2, v110
	v_or_b32_e32 v2, 51, v165
	v_writelane_b32 v255, s21, 34
	v_cmp_gt_i32_e64 s[50:51], v2, v110
	v_or_b32_e32 v2, 64, v165
	v_cmp_gt_i32_e64 s[52:53], v2, v110
	v_or_b32_e32 v2, 0x41, v165
	v_writelane_b32 v255, s36, 35
	v_cmp_gt_i32_e64 s[54:55], v2, v110
	v_or_b32_e32 v2, 0x42, v165
	v_writelane_b32 v255, s31, 36
	v_cmp_gt_i32_e64 s[56:57], v2, v110
	v_or_b32_e32 v2, 0x43, v165
	v_writelane_b32 v255, s31, 37
	v_cmp_gt_i32_e64 s[58:59], v2, v110
	v_or_b32_e32 v2, 0x50, v165
	v_writelane_b32 v255, s34, 38
	s_load_dwordx4 s[84:87], s[34:35], 0x90
	v_cmp_gt_i32_e64 s[60:61], v2, v110
	v_or_b32_e32 v2, 0x70, v211
	v_mad_u32_u24 v12, v1, s28, v12
	v_mad_u32_u24 v13, v1, s28, v13
	v_or_b32_e32 v14, 48, v211
	v_add_u32_e32 v174, s29, v15
	v_add_u32_e32 v190, s29, v8
	v_add_u32_e32 v194, s29, v5
	s_cselect_b64 s[92:93], -1, 0
	s_cmp_gt_i32 s36, 1
	v_mul_u32_u24_e32 v19, 0x110, v2
	v_add_u32_e32 v2, s29, v3
	v_readlane_b32 s29, v254, 6
	s_cselect_b64 s[18:19], -1, 0
	s_cmp_gt_i32 s36, 2
	v_mad_u32_u24 v215, v1, s28, v2
	v_add_u32_e32 v216, v2, v12
	v_add_u32_e32 v217, v2, v13
	v_mad_u32_u24 v218, v14, s28, v2
	v_add_u32_e32 v2, s29, v3
	v_readlane_b32 s29, v254, 7
	s_cselect_b64 s[20:21], -1, 0
	s_cmp_gt_i32 s36, 3
	v_mad_u32_u24 v219, v1, s28, v2
	v_add_u32_e32 v220, v2, v12
	v_add_u32_e32 v221, v2, v13
	v_mad_u32_u24 v222, v14, s28, v2
	v_add_u32_e32 v2, s29, v3
	v_readlane_b32 s29, v254, 8
	v_writelane_b32 v255, s35, 39
	s_cselect_b64 s[22:23], -1, 0
	s_cmp_gt_i32 s36, 4
	v_mad_u32_u24 v223, v1, s28, v2
	v_add_u32_e32 v224, v2, v12
	v_add_u32_e32 v225, v2, v13
	v_mad_u32_u24 v226, v14, s28, v2
	v_add_u32_e32 v2, s29, v3
	s_waitcnt lgkmcnt(0)
; #define LAS __attribute__((address_space(3)))
; __device__ __forceinline__ void ssd_phase(const bf16_t* XBC, const float* DT  , const ss_t* SSq, const float* dtb, const bf16_t* Z, const float* a_log, const float* d_skip, bf16_t* YS, LAS unsigned char* lds, int tid, int wid, int lane, int bid, int G) {
;     const int fr = lane & 15, fq = lane >> 4;
;     LAS bf16_t* Ct = (LAS bf16_t*)(lds + SS_CT); LAS bf16_t* Bt = (LAS bf16_t*)(lds + SS_BT); LAS bf16_t* XT = (LAS bf16_t*)(lds + SS_XT); LAS bf16_t* XW = (LAS bf16_t*)(lds + SS_XW);
;     LAS bf16_t* Sin = (LAS bf16_t*)(lds + SS_SIN); LAS float* csbuf = (LAS float*)(lds + SS_CS);
;     for (int w = bid; w < 256; w += G) {
;         const int b = w >> 6, h = w & 63, g = h >> 3;
;         const float A = -expf(a_log[h]), Dh = d_skip[h], dtbh = dtb[h];
;         f32x4 Sacc[4];
; #pragma unroll
;         for (int pt = 0; pt < 4; ++pt) Sacc[pt] = (f32x4){0.f, 0.f, 0.f, 0.f};
;         u32x4 cr[4], br[4], xr2[2]; float d0 = 0.f, d1 = 0.f;
;         const unsigned voffC = (unsigned)(((tid >> 4) * SSD_CONV + 5120 + g * 128 + (tid & 15) * 8) * 2), voffX = (unsigned)(((tid & 127) * SSD_CONV + h * 64 + (tid >> 7) * 8) * 2);
;     ...
;             const int lrow = 16 * wid + fr; const float csl = csv[lrow];
;             bf16x8 Cfr[4];
; #pragma unroll
;             for (int ks = 0; ks < 4; ++ks) Cfr[ks] = *(const LAS bf16x8*)(Ct + lrow * SS_RS + 32 * ks + 8 * fq);
;             unsigned gp[8][2];
; #pragma unroll
;             for (int t = 0; t < 8; ++t) {
;                 if (t <= wid) {
;                     f32x4 acc = (f32x4){0.f, 0.f, 0.f, 0.f};
; #pragma unroll
;                     for (int ks = 0; ks < 4; ++ks) { const bf16x8 bfr = *(const LAS bf16x8*)(Bt + (16 * t + fr) * SS_RS + 32 * ks + 8 * fq); acc = __builtin_amdgcn_mfma_f32_16x16x32_bf16(bfr, Cfr[ks], acc, 0, 0, 0); }
;                     const f32x4 cs4 = *(const LAS f32x4*)(csv + 16 * t + 4 * fq); float v[4];
; #pragma unroll
;                     for (int r = 0; r < 4; ++r) { const int sx = 16 * t + 4 * fq + r; v[r] = (sx <= lrow) ? acc[r] * __expf(csl - cs4[r]) : 0.f; }
;                     gp[t][0] = cvt_pk_bf16(v[0], v[1]); gp[t][1] = cvt_pk_bf16(v[2], v[3]);
;                 } else { gp[t][0] = 0u; gp[t][1] = 0u; }
;                 __builtin_amdgcn_sched_barrier(0);
	v_writelane_b32 v255, s84, 40
	v_add_u32_e32 v157, s7, v3
	v_mul_lo_u32 v9, v110, s28
	s_movk_i32 s30, 0x3000
	s_cselect_b64 s[24:25], -1, 0
	s_cmp_gt_i32 s36, 5
	v_mad_u32_u24 v227, v1, s28, v2
	v_add_u32_e32 v228, v2, v12
	v_add_u32_e32 v229, v2, v13
	v_mad_u32_u24 v230, v14, s28, v2
	v_mov_b64_e32 v[2:3], 0x1ac00040
	v_writelane_b32 v255, s85, 41
	v_lshlrev_b32_e32 v106, 1, v211
	v_add_u32_e32 v9, 0, v9
	v_add_u32_e32 v164, 0, v10
	v_lshl_add_u32 v11, v1, 1, s6
	v_mul_u32_u24_e32 v168, 0x110, v1
	v_or_b32_e32 v5, 0x51, v165
	v_or_b32_e32 v6, 0x52, v165
	v_or_b32_e32 v8, 0x53, v165
	s_cselect_b64 s[26:27], -1, 0
	v_or_b32_e32 v15, 0x60, v165
	v_or_b32_e32 v16, 0x61, v165
	v_or_b32_e32 v17, 0x62, v165
	v_or_b32_e32 v18, 0x63, v165
	s_cmp_gt_i32 s36, 6
	v_or_b32_e32 v20, 0x70, v165
	v_or_b32_e32 v21, 0x71, v165
	v_or_b32_e32 v22, 0x72, v165
	v_or_b32_e32 v23, 0x73, v165
	v_mul_u32_u24_e32 v1, 0x880, v4
	v_ashrrev_i32_e32 v111, 31, v110
	v_mad_i64_i32 v[124:125], s[28:29], v110, s30, v[2:3]
	v_mov_b32_e32 v2, 0x20e30800
	v_writelane_b32 v255, s86, 42
	v_add_u32_e32 v166, s8, v10
	v_cmp_eq_u32_e64 s[6:7], 0, v211
	v_cmp_gt_u32_e64 s[8:9], 2, v211
	v_cmp_gt_u32_e64 s[10:11], 4, v211
	v_cmp_gt_u32_e64 s[12:13], 8, v211
	v_cmp_gt_u32_e64 s[14:15], 16, v211
	v_cmp_gt_u32_e64 s[16:17], 32, v211
	v_mul_u32_u24_e32 v169, 0x110, v14
	v_add_u32_e32 v231, 0x1400, v7
	v_or_b32_e32 v120, 0x80, v106
	v_lshlrev_b32_e32 v122, 9, v211
	v_mov_b32_e32 v123, v0
	v_lshl_or_b32 v126, v211, 4, v2
	v_mov_b32_e32 v127, v0
	v_lshlrev_b64 v[128:129], 13, v[110:111]
	v_add_u32_e32 v111, v9, v10
	v_add_u32_e32 v232, v164, v19
	v_add_u32_e32 v233, v11, v1
	s_mov_b32 s36, s31
	v_cmp_gt_i32_e64 s[62:63], v5, v110
	v_cmp_gt_i32_e64 s[64:65], v6, v110
	v_cmp_gt_i32_e64 s[66:67], v8, v110
	v_cmp_gt_i32_e64 s[68:69], v15, v110
	v_cmp_gt_i32_e64 s[70:71], v16, v110
	v_cmp_gt_i32_e64 s[72:73], v17, v110
	v_cmp_gt_i32_e64 s[74:75], v18, v110
	s_cselect_b64 s[28:29], -1, 0
	v_cmp_gt_i32_e64 s[76:77], v20, v110
	v_cmp_gt_i32_e64 s[78:79], v21, v110
	v_cmp_gt_i32_e64 s[80:81], v22, v110
	v_cmp_gt_i32_e64 s[82:83], v23, v110
	v_writelane_b32 v255, s87, 43
	s_branch .LBB0_94

; #define LAS __attribute__((address_space(3)))
; __device__ __forceinline__ int xpose_all(const float* src, const float* src2, int ld, int K, int ndst, int nsrc, int mode, bf16_t* dst, int it, int NGW, LAS float* scr, int lane, const float* gvec = nullptr) {
;     const int nblk = ndst / 32, nitems = (K / 64) * nblk;
;     for (; it < nitems; it += NGW) {
;         const int kb = it / nblk, nb = it % nblk, n0 = nb * 32; const float* sp;
;         if (mode == 0) sp = (n0 < nsrc) ? src + n0 : nullptr;
;         else if (mode == 1) { const int unit = n0 >> 8, bj = (n0 >> 7) & 1, cl = n0 & 127; sp = (bj ? src2 : src) + unit * 128 + cl; }
;         else if (mode == 3) { const int pn = n0 >> 8, cl = n0 & 255; sp = src + ((pn >> 2) & 1) * 2048 + ((pn & 3) + 4 * (pn >> 3)) * 256 + cl; }
;         else { const int unit = n0 >> 8, bj = (n0 >> 7) & 1, cl = n0 & 127; sp = (bj ? src2 : src) + (size_t)(unit >> 1) * 65536 + (unit & 1) * 128 + cl; }
;         xpose_item(sp, ld, dst + (size_t)n0 * K, K, kb * 64, scr, lane, gvec);
; __global__ void __launch_bounds__(512) mega(Args a_byval) {
;     ...
;             it = xpose_all(a.in[23] + (size_t)lyr * D * DFF, a.in[24] + (size_t)lyr * D * DFF, DFF, 2048, 2 * DFF, 2 * DFF, 1, (bf16_t*)(ws + (lyr ? WS_W_GU : WS_W_GU0)), it, NGW, scr, lane, norm_ffn_g + lyr * D);
.LBB0_146:
	s_setprio 0
	v_readlane_b32 s72, v255, 7
	v_readlane_b32 s70, v254, 14
	v_readlane_b32 s75, v255, 10
	v_readlane_b32 s78, v254, 16
	v_readlane_b32 s80, v254, 19
	v_readlane_b32 s92, v255, 38
	v_readlane_b32 s69, v254, 13
	v_readlane_b32 s71, v254, 15
	v_readlane_b32 s73, v255, 8
	v_readlane_b32 s74, v255, 9
	v_readlane_b32 s79, v254, 17
	v_readlane_b32 s75, v254, 18
	v_readlane_b32 s81, v254, 20
	s_movk_i32 s82, 0x2000
	s_movk_i32 s83, 0x1800
	s_mov_b32 s84, 0x16000
	s_movk_i32 s85, 0x3000
	s_mov_b32 s87, 0x1ac03000
	s_mov_b32 s88, 0x1ac06000
	s_mov_b32 s89, 0xfffe0
	s_movk_i32 s90, 0xa1
	s_mov_b32 s91, 0x80000
	v_readlane_b32 s93, v255, 39
	v_readlane_b32 s94, v255, 37
	v_readlane_b32 s95, v255, 35
	v_readlane_b32 s76, v255, 6
	v_readlane_b32 s59, v255, 5
	s_cmpk_lg_i32 s59, 0x100
	s_cbranch_scc1 .Lsgx_done
	s_cmpk_lt_i32 s94, 0x80
	s_cbranch_scc1 .Lsgx_done
	s_waitcnt lgkmcnt(0)
	s_barrier
	s_lshl_b32 s59, s94, 3
	s_add_i32 s59, s59, s95
	s_mul_i32 s64, s95, 0x2100
	v_and_b32_e32 v2, 31, v200
	v_lshrrev_b32_e32 v3, 5, v200
	v_lshlrev_b32_e32 v4, 2, v2
	v_mul_u32_u24_e32 v6, 0x84, v3
	v_add3_u32 v6, v6, v4, s64
	v_and_b32_e32 v7, 7, v200
	v_lshrrev_b32_e32 v8, 3, v200
	v_mul_u32_u24_e32 v9, 0x420, v7
	v_lshl_add_u32 v9, v8, 2, v9
	v_add_u32_e32 v9, s64, v9
	s_cmpk_ge_i32 s59, 0x2c00
	s_cbranch_scc1 .Lxpgx_end
	s_load_dwordx2 s[60:61], s[92:93], 0xb8
	s_load_dwordx2 s[62:63], s[92:93], 0xe8
	s_load_dwordx2 s[64:65], s[92:93], 0x18
	v_mov_b32_e32 v5, 0x5800
	v_mul_u32_u24_e32 v5, v3, v5
	v_add_u32_e32 v5, v5, v4
	v_mov_b32_e32 v10, 0x1000
	v_mul_u32_u24_e32 v10, v8, v10
	v_lshl_add_u32 v12, v7, 4, v10
	v_add_u32_e32 v13, 0x8000, v12
	v_add_u32_e32 v14, 0x10000, v12
	v_add_u32_e32 v15, 0x18000, v12
	s_waitcnt lgkmcnt(0)
	s_add_u32 s62, s62, 0x3900000
	s_addc_u32 s63, s63, 0
	s_add_u32 s64, s64, 0x2000
	s_addc_u32 s65, s65, 0
	v_lshlrev_b32_e32 v16, 5, v7
	v_mov_b32_e32 v17, v0
	v_lshl_add_u64 v[16:17], s[64:65], 0, v[16:17]
	s_mul_hi_u32 s64, s59, 0xba2e8c
	s_mul_i32 s65, s64, 0x160
	s_sub_i32 s65, s59, s65
	s_mul_i32 s68, s64, 0x160000
	s_lshr_b32 s66, s65, 3
	s_lshl_b32 s66, s66, 9
	s_add_i32 s68, s68, s66
	s_and_b32 s66, s65, 3
	s_lshl_b32 s66, s66, 7
	s_add_i32 s68, s68, s66
	s_add_i32 s68, s68, 0x2c00000
	s_bitcmp1_b32 s65, 2
	s_movk_i32 s33, 0xb8
	s_cselect_b32 s33, 0xc0, s33
	s_load_dwordx2 s[66:67], s[92:93], s33
	s_waitcnt lgkmcnt(0)
	s_add_u32 s66, s66, s68
	s_addc_u32 s67, s67, 0
	s_lshl_b32 s64, s64, 8
	s_mov_b32 s65, 0
	v_lshl_add_u64 v[18:19], s[64:65], 0, v[16:17]
	global_load_dwordx4 v[52:55], v[18:19], off
	global_load_dwordx4 v[56:59], v[18:19], off offset:16
	v_mov_b32_e32 v11, v5
	global_load_dword v20, v11, s[66:67] nt
	v_add_u32_e32 v11, 0xb000, v11
	global_load_dword v21, v11, s[66:67] nt
	v_add_u32_e32 v11, 0xb000, v11
	global_load_dword v22, v11, s[66:67] nt
	v_add_u32_e32 v11, 0xb000, v11
	global_load_dword v23, v11, s[66:67] nt
	v_add_u32_e32 v11, 0xb000, v11
	global_load_dword v24, v11, s[66:67] nt
	v_add_u32_e32 v11, 0xb000, v11
	global_load_dword v25, v11, s[66:67] nt
	v_add_u32_e32 v11, 0xb000, v11
	global_load_dword v26, v11, s[66:67] nt
	v_add_u32_e32 v11, 0xb000, v11
	global_load_dword v27, v11, s[66:67] nt
	v_add_u32_e32 v11, 0xb000, v11
	global_load_dword v28, v11, s[66:67] nt
	v_add_u32_e32 v11, 0xb000, v11
	global_load_dword v29, v11, s[66:67] nt
	v_add_u32_e32 v11, 0xb000, v11
	global_load_dword v30, v11, s[66:67] nt
	v_add_u32_e32 v11, 0xb000, v11
	global_load_dword v31, v11, s[66:67] nt
	v_add_u32_e32 v11, 0xb000, v11
	global_load_dword v32, v11, s[66:67] nt
	v_add_u32_e32 v11, 0xb000, v11
	global_load_dword v33, v11, s[66:67] nt
	v_add_u32_e32 v11, 0xb000, v11
	global_load_dword v34, v11, s[66:67] nt
	v_add_u32_e32 v11, 0xb000, v11
	global_load_dword v35, v11, s[66:67] nt
	v_add_u32_e32 v11, 0xb000, v11
	global_load_dword v36, v11, s[66:67] nt
	v_add_u32_e32 v11, 0xb000, v11
	global_load_dword v37, v11, s[66:67] nt
	v_add_u32_e32 v11, 0xb000, v11
	global_load_dword v38, v11, s[66:67] nt
	v_add_u32_e32 v11, 0xb000, v11
	global_load_dword v39, v11, s[66:67] nt
	v_add_u32_e32 v11, 0xb000, v11
	global_load_dword v40, v11, s[66:67] nt
	v_add_u32_e32 v11, 0xb000, v11
	global_load_dword v41, v11, s[66:67] nt
	v_add_u32_e32 v11, 0xb000, v11
	global_load_dword v42, v11, s[66:67] nt
	v_add_u32_e32 v11, 0xb000, v11
	global_load_dword v43, v11, s[66:67] nt
	v_add_u32_e32 v11, 0xb000, v11
	global_load_dword v44, v11, s[66:67] nt
	v_add_u32_e32 v11, 0xb000, v11
	global_load_dword v45, v11, s[66:67] nt
	v_add_u32_e32 v11, 0xb000, v11
	global_load_dword v46, v11, s[66:67] nt
	v_add_u32_e32 v11, 0xb000, v11
	global_load_dword v47, v11, s[66:67] nt
	v_add_u32_e32 v11, 0xb000, v11
	global_load_dword v48, v11, s[66:67] nt
	v_add_u32_e32 v11, 0xb000, v11
	global_load_dword v49, v11, s[66:67] nt
	v_add_u32_e32 v11, 0xb000, v11
	global_load_dword v50, v11, s[66:67] nt
	v_add_u32_e32 v11, 0xb000, v11
	global_load_dword v51, v11, s[66:67] nt
